# one static s_setprio 1 for waves 4-7 at kernel entry (younger half of each SIMD pair)
# speedup vs baseline: 1.0257x; 1.0013x over previous
; DI int tid_opaque() { int t = threadIdx.x; asm volatile("" : "+v"(t)); return t; }
; DI u32x2 pack4(float a, float b, float c, float d) { u32x2 r; r.x = pack2(a, b); r.y = pack2(c, d); return r; }
; DI void prep_rows(const Params& p) {
;   const int tt_ = tid_opaque();
;   const int l = tt_ & 63, gw = blockIdx.x * 8 + (tt_ >> 6), nw = gridDim.x * 8;
;   for (int row = gw; row < T_TOK; row += nw) {
;     const float* src = row < TP ? p.x_prompt + (long)row * 1024 : p.x_sample + (long)(row - TP) * 1024;
;     float4 v[4];
;     float s = 0.f;
; #pragma unroll
;     for (int i = 0; i < 4; ++i) {
;       v[i] = ((const float4*)src)[l + 64 * i];
;       s += v[i].x * v[i].x + v[i].y * v[i].y + v[i].z * v[i].z + v[i].w * v[i].w;
;     }
; #pragma unroll
;     for (int o = 1; o < 64; o <<= 1) s += __shfl_xor(s, o);
; #pragma unroll
;     for (int i = 0; i < 4; ++i) {
;       *(u32x2*)(p.buf0 + (long)row * 1024 + (l + 64 * i) * 4) = pack4(v[i].x, v[i].y, v[i].z, v[i].w);
;     }
;     if (l == 0) p.ssq[row] = s;
_Z14fwd_megakernel6Params:
	s_load_dword s42, s[0:1], 0x8a8
	v_readfirstlane_b32 s98, v0
	s_nop 3
	s_and_b32 s98, s98, 0x3ff
	s_lshr_b32 s98, s98, 6
	s_cmp_ge_u32 s98, 4
	s_cbranch_scc0 .Lprio_done
	s_setprio 1
.Lprio_done:
	v_and_b32_e32 v182, 0x3ff, v0
	s_add_u32 s96, s0, 0x8a8
	v_mov_b32_e32 v1, v182
	s_addc_u32 s97, s1, 0
	s_lshl_b32 s92, s2, 3
	v_ashrrev_i32_e32 v2, 6, v1
	v_add_u32_e32 v2, s92, v2
	s_mov_b32 s3, 0x14000
	s_mov_b32 s82, s2
	s_waitcnt lgkmcnt(0)
	s_lshl_b32 s34, s42, 3
	v_cmp_gt_i32_e32 vcc, s3, v2
	v_mbcnt_lo_u32_b32 v183, -1, 0
	s_and_saveexec_b64 s[8:9], vcc
	s_cbranch_execz .LBB0_7
	v_mbcnt_hi_u32_b32 v3, -1, v183
	v_and_b32_e32 v10, 63, v1
	v_and_b32_e32 v1, 64, v3
	v_add_u32_e32 v4, 64, v1
	v_xor_b32_e32 v1, 1, v3
	v_cmp_lt_i32_e64 s[4:5], v1, v4
	v_xor_b32_e32 v6, 2, v3
	s_load_dwordx2 s[10:11], s[0:1], 0x60
	v_cndmask_b32_e64 v1, v3, v1, s[4:5]
	v_cmp_lt_i32_e64 s[4:5], v6, v4
	v_mov_b32_e32 v5, 0
	s_ashr_i32 s35, s34, 31
	v_cndmask_b32_e64 v6, v3, v6, s[4:5]
	v_lshlrev_b32_e32 v16, 2, v6
	v_xor_b32_e32 v6, 4, v3
	v_cmp_lt_i32_e64 s[4:5], v6, v4
	v_cmp_eq_u32_e32 vcc, 0, v10
	v_lshlrev_b32_e32 v1, 2, v1
	v_cndmask_b32_e64 v6, v3, v6, s[4:5]
	v_lshlrev_b32_e32 v17, 2, v6
	v_xor_b32_e32 v6, 8, v3
	v_cmp_lt_i32_e64 s[4:5], v6, v4
	s_lshl_b64 s[12:13], s[34:35], 12
	s_mov_b64 s[14:15], 0
	v_cndmask_b32_e64 v6, v3, v6, s[4:5]
	v_lshlrev_b32_e32 v18, 2, v6
	v_xor_b32_e32 v6, 16, v3
	v_cmp_lt_i32_e64 s[4:5], v6, v4
	s_movk_i32 s3, 0x3fff
	v_mov_b32_e32 v11, v5
	v_cndmask_b32_e64 v6, v3, v6, s[4:5]
	v_lshlrev_b32_e32 v19, 2, v6
	v_xor_b32_e32 v6, 32, v3
	v_cmp_lt_i32_e64 s[4:5], v6, v4
	v_lshlrev_b32_e32 v4, 3, v10
	v_lshlrev_b32_e32 v10, 4, v10
	v_cndmask_b32_e64 v3, v3, v6, s[4:5]
	s_load_dwordx4 s[4:7], s[0:1], 0x0
	s_waitcnt lgkmcnt(0)
	v_lshl_add_u64 v[6:7], s[10:11], 0, v[4:5]
	s_load_dwordx2 s[10:11], s[0:1], 0xf8
	v_lshlrev_b32_e32 v20, 2, v3
	v_ashrrev_i32_e32 v3, 31, v2
	v_lshlrev_b64 v[8:9], 12, v[2:3]
	v_lshl_add_u64 v[8:9], s[4:5], 0, v[8:9]
	s_mov_b32 s18, 0x13fff
	s_branch .LBB0_3
